# scan consumer: half-wave gather via v_permlane32_swap on register copies instead of 8 ds_bpermute round trips + 16 v_cndmask
# baseline (speedup 1.0000x reference)
; __device__ __forceinline__ void scan_unit_mfma(const TI ti, CArgs& a, int l, int u, bool ctx_out, unsigned char* ldsg) {
;     ...
;                 LAS const unsigned char* buf = L + (C % RING) * BUFB;
;                 const bf16x8 xb0 = *(LAS const bf16x8*)(buf + O_XF + lane * 16), xb1 = *(LAS const bf16x8*)(buf + O_XF + 1024 + lane * 16);
;                 f32x16 Z;
; #pragma unroll
;                 for (int i = 0; i < 16; ++i) Z[i] = 0.f;
; #pragma unroll
;                 for (int jt = 0; jt < 2; ++jt) {
; #pragma unroll
;                     for (int s = 0; s < 2; ++s) {
;                         LAS const unsigned char* ap = buf + O_AR + r * 144 + (32 * jt + 16 * s + 4 * h) * 2;
;                         const s16x4 lo = *(LAS const s16x4*)ap, hi = *(LAS const s16x4*)(ap + 16);
;                         const bf16x8 a2 = __builtin_shufflevector(lo, hi, 0, 1, 2, 3, 4, 5, 6, 7);
;                         const bf16x8 stp = jt == 0 ? pk8f(ST0[8 * s], ST0[8 * s + 1], ST0[8 * s + 2], ST0[8 * s + 3], ST0[8 * s + 4], ST0[8 * s + 5], ST0[8 * s + 6], ST0[8 * s + 7])
;                                                    : pk8f(ST1[8 * s], ST1[8 * s + 1], ST1[8 * s + 2], ST1[8 * s + 3], ST1[8 * s + 4], ST1[8 * s + 5], ST1[8 * s + 6], ST1[8 * s + 7]);
;                         Z = MFMA32(a2, stp, Z);
;                     }
;                 }
;                 LAS const unsigned char* vp = buf + O_VTT + (32 * it + r) * 48;
;                 {
;                     const s16x4 lo = *(LAS const s16x4*)(vp + 8 * h), hi = *(LAS const s16x4*)(vp + 16 + 8 * h);
;                     const bf16x8 vf = __builtin_shufflevector(lo, hi, 0, 1, 2, 3, 4, 5, 6, 7);
;                     Z = MFMA32(xb1, vf, Z);
;                 }
;                 float o[8], g[16], uu[16];
; #pragma unroll
;                 for (int q = 0; q < 8; ++q) o[q] = __shfl_xor(Z[q], 32);
; #pragma unroll
;                 for (int e = 0; e < 4; ++e) {
;                     g[e] = h ? o[e] : Z[e]; g[4 + e] = h ? Z[e] : o[e];
;                     g[8 + e] = h ? o[4 + e] : Z[4 + e]; g[12 + e] = h ? Z[4 + e] : o[4 + e];
;                 }
;                 {
;                     LAS const float* NS = (LAS const float*)(buf + O_NS);
; #pragma unroll
;                     for (int t = 0; t < 16; ++t) uu[t] = g[t];
; #pragma unroll
;                     for (int s = 0; s < 15; ++s) {
; #pragma unroll
.LBB0_323:
	s_add_i32 s4, s14, 22
	s_cmp_lt_u32 s4, 6
	s_cbranch_scc1 .LBB0_322
	s_add_i32 s1, s14, 16
	s_and_b32 s3, s1, 0xff
	s_mulk_i32 s3, 0xab
	s_bfe_u32 s3, s3, 0x6000a
	s_mul_i32 s3, s3, 6
	s_sub_i32 s1, s1, s3
	s_and_b32 s1, s1, 0xff
	s_mulk_i32 s1, 0x5100
	s_add_i32 s17, s1, 0
	v_add3_u32 v0, s17, v85, v91
	ds_read2_b64 v[2:5], v0 offset1:2
	v_cvt_pk_bf16_f32 v6, v16, v17
	v_cvt_pk_bf16_f32 v7, v18, v19
	v_cvt_pk_bf16_f32 v8, v20, v21
	v_cvt_pk_bf16_f32 v9, v22, v23
	ds_read2_b64 v[10:13], v0 offset0:12 offset1:14
	v_add_u32_e32 v14, s17, v89
	v_mov_b32_e32 v109, s17
	s_movk_i32 s18, 0xff
	s_waitcnt lgkmcnt(1)
	v_mfma_f32_32x32x16_bf16 v[48:63], v[2:5], v[6:9], 0
	ds_read2_b64 v[2:5], v0 offset0:4 offset1:6
	v_cvt_pk_bf16_f32 v6, v24, v25
	v_cvt_pk_bf16_f32 v7, v26, v27
	v_cvt_pk_bf16_f32 v8, v28, v29
	v_cvt_pk_bf16_f32 v9, v30, v31
	s_cmp_lt_u32 s4, 22
	s_waitcnt lgkmcnt(0)
	v_mfma_f32_32x32x16_bf16 v[48:63], v[2:5], v[6:9], v[48:63]
	ds_read2_b64 v[2:5], v0 offset0:8 offset1:10
	v_cvt_pk_bf16_f32 v6, v32, v33
	v_cvt_pk_bf16_f32 v7, v34, v35
	v_cvt_pk_bf16_f32 v8, v36, v37
	v_cvt_pk_bf16_f32 v9, v38, v39
	v_add_u32_e32 v0, s17, v98
	s_waitcnt lgkmcnt(0)
	v_mfma_f32_32x32x16_bf16 v[48:63], v[2:5], v[6:9], v[48:63]
	v_cvt_pk_bf16_f32 v2, v40, v41
	v_cvt_pk_bf16_f32 v3, v42, v43
	v_cvt_pk_bf16_f32 v4, v44, v45
	v_cvt_pk_bf16_f32 v5, v46, v47
	ds_read_b128 v[6:9], v14 offset:19712
	s_nop 0
	v_mfma_f32_32x32x16_bf16 v[48:63], v[10:13], v[2:5], v[48:63]
	v_add_u32_e32 v2, v0, v91
	v_add_u32_e32 v2, 0x3800, v2
	ds_read2_b64 v[10:13], v2 offset1:2
	ds_read_b128 v[2:5], v14 offset:18688
	s_waitcnt lgkmcnt(1)
	v_mfma_f32_32x32x16_bf16 v[48:63], v[6:9], v[10:13], v[48:63]
	s_nop 11
	v_mov_b32_e32 v101, v51
	v_mov_b32_e32 v99, v51
	v_mov_b32_e32 v103, v55
	v_mov_b32_e32 v102, v55
	v_mov_b32_e32 v108, v48
	v_mov_b32_e32 v6, v48
	v_mov_b32_e32 v11, v49
	v_mov_b32_e32 v8, v49
	v_mov_b32_e32 v15, v50
	v_mov_b32_e32 v12, v50
	v_mov_b32_e32 v10, v52
	v_mov_b32_e32 v7, v52
	v_mov_b32_e32 v13, v53
	v_mov_b32_e32 v9, v53
	v_mov_b32_e32 v100, v54
	v_mov_b32_e32 v14, v54
	s_nop 1
	v_permlane32_swap_b32 v101, v99
	v_permlane32_swap_b32 v103, v102
	v_permlane32_swap_b32 v108, v6
	v_permlane32_swap_b32 v11, v8
	v_permlane32_swap_b32 v15, v12
	v_permlane32_swap_b32 v10, v7
	v_permlane32_swap_b32 v13, v9
	v_permlane32_swap_b32 v100, v14
	ds_read_b128 v[64:67], v109 offset:17696
	ds_read_b128 v[68:71], v109 offset:17712
	ds_read_b128 v[72:75], v109 offset:17664
	ds_read_b128 v[76:79], v109 offset:17680
	s_waitcnt lgkmcnt(1)
	v_fmac_f32_e32 v11, v73, v108
	v_fmac_f32_e32 v15, v74, v108
	v_fmac_f32_e32 v101, v75, v108
	s_waitcnt lgkmcnt(0)
	v_fmac_f32_e32 v6, v76, v108
	v_fmac_f32_e32 v8, v77, v108
	v_fmac_f32_e32 v12, v78, v108
	v_fmac_f32_e32 v99, v79, v108
	v_fmac_f32_e32 v10, v64, v108
	v_fmac_f32_e32 v13, v65, v108
	v_fmac_f32_e32 v100, v66, v108
	v_fmac_f32_e32 v103, v67, v108
	ds_read_b128 v[64:67], v109 offset:17760
	ds_read_b128 v[72:75], v109 offset:17776
	ds_read_b128 v[76:79], v109 offset:17728
	ds_read_b128 v[104:107], v109 offset:17744
	v_fmac_f32_e32 v9, v69, v108
	v_fmac_f32_e32 v7, v68, v108
	v_fmac_f32_e32 v14, v70, v108
	v_fmac_f32_e32 v102, v71, v108
	s_waitcnt lgkmcnt(1)
	v_fmac_f32_e32 v15, v78, v11
	v_fmac_f32_e32 v101, v79, v11
	s_waitcnt lgkmcnt(0)
	v_fmac_f32_e32 v6, v104, v11
	v_fmac_f32_e32 v8, v105, v11
	v_fmac_f32_e32 v12, v106, v11
	v_fmac_f32_e32 v99, v107, v11
	v_fmac_f32_e32 v10, v64, v11
	v_fmac_f32_e32 v13, v65, v11
	v_fmac_f32_e32 v100, v66, v11
	v_fmac_f32_e32 v103, v67, v11
	ds_read_b128 v[64:67], v109 offset:17824
	ds_read_b128 v[68:71], v109 offset:17840
	ds_read_b128 v[76:79], v109 offset:17792
	ds_read_b128 v[104:107], v109 offset:17808
	v_fmac_f32_e32 v9, v73, v11
	v_fmac_f32_e32 v7, v72, v11
	v_fmac_f32_e32 v14, v74, v11
	v_fmac_f32_e32 v102, v75, v11
	s_waitcnt lgkmcnt(3)
	v_fmac_f32_e32 v10, v64, v15
	v_fmac_f32_e32 v13, v65, v15
	v_fmac_f32_e32 v100, v66, v15
	v_fmac_f32_e32 v103, v67, v15
	ds_read_b128 v[64:67], v109 offset:17904
	ds_read_b128 v[72:75], v109 offset:17872
	s_waitcnt lgkmcnt(4)
	v_fmac_f32_e32 v9, v69, v15
	s_waitcnt lgkmcnt(3)
	v_fmac_f32_e32 v101, v79, v15
	v_fmac_f32_e32 v7, v68, v15
	v_fmac_f32_e32 v14, v70, v15
	v_fmac_f32_e32 v102, v71, v15
	ds_read_b128 v[68:71], v109 offset:17888
	ds_read_b128 v[76:79], v109 offset:17936
	s_waitcnt lgkmcnt(4)
; #define LAS __attribute__((address_space(3)))
; #define MFMA32(a, b, c) __builtin_amdgcn_mfma_f32_32x32x16_bf16((a), (b), (c), 0, 0, 0)
; __device__ __forceinline__ void scan_unit_mfma(const TI ti, CArgs& a, int l, int u, bool ctx_out, unsigned char* ldsg) {
;     ...
; #pragma unroll
;                     for (int s = 0; s < 15; ++s) {
; #pragma unroll
;                         for (int t4 = (s + 1) / 4; t4 < 4; ++t4) {
;                             const f32x4 nv = *(LAS const f32x4*)(NS + s * 16 + 4 * t4);
;                             if (4 * t4 + 0 > s) uu[4 * t4 + 0] = __builtin_fmaf(nv.x, uu[s], uu[4 * t4 + 0]);
;                             if (4 * t4 + 1 > s) uu[4 * t4 + 1] = __builtin_fmaf(nv.y, uu[s], uu[4 * t4 + 1]);
;                             if (4 * t4 + 2 > s) uu[4 * t4 + 2] = __builtin_fmaf(nv.z, uu[s], uu[4 * t4 + 2]);
;                             if (4 * t4 + 3 > s) uu[4 * t4 + 3] = __builtin_fmaf(nv.w, uu[s], uu[4 * t4 + 3]);
;                         }
;                     }
;                 }
;                 {
;                     const bf16x8 uf = pk8f(h ? uu[4] : uu[0], h ? uu[5] : uu[1], h ? uu[6] : uu[2], h ? uu[7] : uu[3],
;                                            h ? uu[12] : uu[8], h ? uu[13] : uu[9], h ? uu[14] : uu[10], h ? uu[15] : uu[11]);
;                     Z = MFMA32(xb0, uf, Z);
	v_fmac_f32_e32 v6, v104, v15
	v_fmac_f32_e32 v8, v105, v15
	v_fmac_f32_e32 v12, v106, v15
	v_fmac_f32_e32 v99, v107, v15
	s_waitcnt lgkmcnt(2)
	v_fmac_f32_e32 v6, v72, v101
	v_fmac_f32_e32 v8, v73, v101
	v_fmac_f32_e32 v12, v74, v101
	v_fmac_f32_e32 v99, v75, v101
	ds_read_b128 v[72:75], v109 offset:17952
	ds_read_b128 v[104:107], v109 offset:17968
	v_fmac_f32_e32 v9, v65, v101
	s_waitcnt lgkmcnt(3)
	v_fmac_f32_e32 v10, v68, v101
	v_fmac_f32_e32 v13, v69, v101
	v_fmac_f32_e32 v100, v70, v101
	v_fmac_f32_e32 v103, v71, v101
	v_fmac_f32_e32 v7, v64, v101
	v_fmac_f32_e32 v14, v66, v101
	v_fmac_f32_e32 v102, v67, v101
	ds_read_b128 v[64:67], v109 offset:18032
	ds_read_b128 v[68:71], v109 offset:18000
	s_waitcnt lgkmcnt(4)
	v_fmac_f32_e32 v8, v77, v6
	v_fmac_f32_e32 v12, v78, v6
	v_fmac_f32_e32 v99, v79, v6
	s_waitcnt lgkmcnt(3)
	v_fmac_f32_e32 v10, v72, v6
	v_fmac_f32_e32 v13, v73, v6
	v_fmac_f32_e32 v100, v74, v6
	v_fmac_f32_e32 v103, v75, v6
	ds_read_b128 v[72:75], v109 offset:18016
	ds_read_b128 v[76:79], v109 offset:18064
	s_waitcnt lgkmcnt(4)
	v_fmac_f32_e32 v9, v105, v6
	v_fmac_f32_e32 v7, v104, v6
	v_fmac_f32_e32 v14, v106, v6
	v_fmac_f32_e32 v102, v107, v6
	s_waitcnt lgkmcnt(2)
	v_fmac_f32_e32 v12, v70, v8
	v_fmac_f32_e32 v99, v71, v8
	ds_read_b128 v[68:71], v109 offset:18080
	ds_read_b128 v[104:107], v109 offset:18096
	v_fmac_f32_e32 v9, v65, v8
	s_waitcnt lgkmcnt(3)
	v_fmac_f32_e32 v10, v72, v8
	v_fmac_f32_e32 v13, v73, v8
	v_fmac_f32_e32 v100, v74, v8
	v_fmac_f32_e32 v103, v75, v8
	v_fmac_f32_e32 v7, v64, v8
	v_fmac_f32_e32 v14, v66, v8
	v_fmac_f32_e32 v102, v67, v8
	ds_read_b128 v[64:67], v109 offset:18144
	ds_read_b128 v[72:75], v109 offset:18160
	s_waitcnt lgkmcnt(4)
	v_fmac_f32_e32 v99, v79, v12
	s_waitcnt lgkmcnt(3)
	v_fmac_f32_e32 v10, v68, v12
	v_fmac_f32_e32 v13, v69, v12
	v_fmac_f32_e32 v100, v70, v12
	v_fmac_f32_e32 v103, v71, v12
	ds_read_b128 v[68:71], v109 offset:18208
	ds_read_b128 v[76:79], v109 offset:18224
	s_waitcnt lgkmcnt(4)
	v_fmac_f32_e32 v9, v105, v12
	v_fmac_f32_e32 v7, v104, v12
	v_fmac_f32_e32 v14, v106, v12
	v_fmac_f32_e32 v102, v107, v12
	s_waitcnt lgkmcnt(2)
	v_fmac_f32_e32 v9, v73, v99
	v_fmac_f32_e32 v10, v64, v99
	v_fmac_f32_e32 v13, v65, v99
	v_fmac_f32_e32 v100, v66, v99
	v_fmac_f32_e32 v103, v67, v99
	v_fmac_f32_e32 v7, v72, v99
	v_fmac_f32_e32 v14, v74, v99
	v_fmac_f32_e32 v102, v75, v99
	ds_read_b128 v[64:67], v109 offset:18272
	ds_read_b128 v[72:75], v109 offset:18288
	s_waitcnt lgkmcnt(2)
	v_fmac_f32_e32 v9, v77, v10
	v_fmac_f32_e32 v13, v69, v10
	v_fmac_f32_e32 v100, v70, v10
	v_fmac_f32_e32 v103, v71, v10
	v_fmac_f32_e32 v7, v76, v10
	v_fmac_f32_e32 v14, v78, v10
	v_fmac_f32_e32 v102, v79, v10
	ds_read_b128 v[68:71], v109 offset:18336
	ds_read_b128 v[76:79], v109 offset:18352
	s_waitcnt lgkmcnt(3)
	v_fmac_f32_e32 v100, v66, v13
	v_fmac_f32_e32 v103, v67, v13
	ds_read_b128 v[64:67], v109 offset:18416
	s_waitcnt lgkmcnt(3)
	v_fmac_f32_e32 v9, v73, v13
	v_fmac_f32_e32 v7, v72, v13
	v_fmac_f32_e32 v14, v74, v13
	v_fmac_f32_e32 v102, v75, v13
	s_waitcnt lgkmcnt(1)
	v_fmac_f32_e32 v9, v77, v100
	v_fmac_f32_e32 v103, v71, v100
	v_fmac_f32_e32 v7, v76, v100
	v_fmac_f32_e32 v14, v78, v100
	v_fmac_f32_e32 v102, v79, v100
	ds_read_b128 v[68:71], v109 offset:18480
	s_waitcnt lgkmcnt(1)
	v_fmac_f32_e32 v9, v65, v103
	v_fmac_f32_e32 v7, v64, v103
	v_fmac_f32_e32 v14, v66, v103
	v_fmac_f32_e32 v102, v67, v103
	ds_read_b128 v[64:67], v109 offset:18544
	ds_read_b128 v[72:75], v109 offset:18608
	s_waitcnt lgkmcnt(2)
	v_fmac_f32_e32 v9, v69, v7
	v_fmac_f32_e32 v14, v70, v7
	v_fmac_f32_e32 v102, v71, v7
	s_waitcnt lgkmcnt(1)
	v_fmac_f32_e32 v14, v66, v9
	v_fmac_f32_e32 v102, v67, v9
	s_waitcnt lgkmcnt(0)
	v_fmac_f32_e32 v102, v75, v14
	v_cndmask_b32_e64 v64, v6, v48, s[58:59]
	v_cndmask_b32_e64 v65, v8, v11, s[58:59]
	v_cndmask_b32_e64 v66, v12, v15, s[58:59]
	v_cndmask_b32_e64 v67, v99, v101, s[58:59]
	v_cndmask_b32_e64 v68, v7, v10, s[58:59]
	v_cndmask_b32_e64 v69, v9, v13, s[58:59]
	v_cndmask_b32_e64 v70, v14, v100, s[58:59]
	v_cndmask_b32_e64 v71, v102, v103, s[58:59]
	v_cvt_pk_bf16_f32 v104, v64, v65
	v_cvt_pk_bf16_f32 v105, v66, v67
	v_cvt_pk_bf16_f32 v106, v68, v69
	v_cvt_pk_bf16_f32 v107, v70, v71
	s_nop 1
	v_mfma_f32_32x32x16_bf16 v[64:79], v[2:5], v[104:107], v[48:63]
	s_cbranch_scc1 .LBB0_326
	s_movk_i32 s18, 0x7ff
	s_mov_b32 s3, s14
	s_mov_b32 s1, s7
	s_branch .LBB0_327
